# P1 modulate loop: shift/scale vector loads of column blocks 1..3 hoisted to the top of the iteration, vmcnt(1)/vmcnt(0) pairs behind the stores replaced by counted waits (on top of early buffer_inv +
# speedup vs baseline: 1.0039x; 1.0003x over previous
.LBB0_119:
	s_add_i32 s14, s8, -3
	s_add_i32 s3, s8, 0xffffdffd
	s_cmpk_lt_i32 s0, 0x800
	s_cselect_b64 s[4:5], -1, 0
	s_and_b64 s[4:5], s[4:5], exec
	s_cselect_b32 s9, s53, s55
	s_cselect_b32 s26, s52, s54
	s_ashr_i32 s15, s14, 31
	s_cmpk_lt_i32 s0, 0x800
	s_cselect_b64 s[4:5], -1, 0
	s_and_b64 s[4:5], s[4:5], exec
	s_cselect_b32 s5, s15, 0
	s_cselect_b32 s4, s14, s3
	s_lshr_b32 s3, s3, 10
	s_mul_i32 s3, s3, 6
	s_add_i32 s3, s3, 6
	s_cmpk_lt_i32 s0, 0x800
	s_cselect_b64 s[22:23], -1, 0
	s_and_b64 vcc, s[22:23], exec
	s_cselect_b32 s10, 0, s3
	s_lshl_b64 s[22:23], s[10:11], 12
	s_add_u32 s24, s6, s22
	s_addc_u32 s25, s7, s23
	s_lshl_b64 s[4:5], s[4:5], 12
	v_lshl_add_u64 v[38:39], v[36:37], 0, s[22:23]
	s_add_u32 s22, s26, s4
	v_lshl_add_u64 v[2:3], s[24:25], 0, v[34:35]
	s_addc_u32 s23, s9, s5
	v_add_co_u32_e64 v6, s[4:5], s17, v2
	v_lshl_add_u64 v[40:41], v[2:3], 0, s[12:13]
	s_nop 0
	v_addc_co_u32_e64 v7, s[4:5], 0, v3, s[4:5]
	global_load_dwordx4 v[42:45], v34, s[22:23] nt
	global_load_dwordx4 v[46:49], v34, s[22:23] offset:1024 nt
	global_load_dwordx4 v[22:25], v34, s[22:23] offset:2048 nt
	global_load_dwordx4 v[2:5], v34, s[22:23] offset:3072 nt
	global_load_dwordx4 v[50:53], v[6:7], off
	global_load_dwordx4 v[54:57], v[38:39], off
	global_load_dwordx4 v[100:103], v[40:41], off offset:1024
	global_load_dwordx4 v[104:107], v[38:39], off offset:1024
	global_load_dwordx4 v[108:111], v[40:41], off offset:2048
	global_load_dwordx4 v[112:115], v[38:39], off offset:2048
	global_load_dwordx4 v[116:119], v[40:41], off offset:3072
	global_load_dwordx4 v[120:123], v[38:39], off offset:3072
	v_lshl_add_u64 v[8:9], s[22:23], 0, v[34:35]
	v_add_co_u32_e64 v10, s[4:5], s17, v8
	s_lshl_b64 s[14:15], s[14:15], 11
	s_nop 0
	v_addc_co_u32_e64 v11, s[4:5], 0, v9, s[4:5]
	v_add_co_u32_e64 v12, s[4:5], s18, v8
	s_add_u32 s14, s1, s14
	s_nop 0
	v_addc_co_u32_e64 v13, s[4:5], 0, v9, s[4:5]
	v_add_co_u32_e64 v14, s[4:5], s19, v8
	s_addc_u32 s15, s16, s15
	s_nop 0
	v_addc_co_u32_e64 v15, s[4:5], 0, v9, s[4:5]
	global_load_dwordx4 v[58:61], v[12:13], off offset:-4096 nt
	global_load_dwordx4 v[62:65], v[12:13], off nt
	global_load_dwordx4 v[66:69], v[14:15], off nt
	global_load_dwordx4 v[6:9], v[10:11], off offset:3072 nt
	global_load_dwordx4 v[70:73], v[10:11], off offset:1024 nt
	global_load_dwordx4 v[30:33], v[10:11], off offset:2048 nt
	global_load_dwordx4 v[74:77], v[12:13], off offset:1024 nt
	global_load_dwordx4 v[26:29], v[12:13], off offset:2048 nt
	s_nop 0
	global_load_dwordx4 v[10:13], v[12:13], off offset:3072 nt
	s_nop 0
	global_load_dwordx4 v[78:81], v[14:15], off offset:1024 nt
	global_load_dwordx4 v[18:21], v[14:15], off offset:2048 nt
	s_nop 0
	global_load_dwordx4 v[14:17], v[14:15], off offset:3072 nt
	s_add_i32 s4, s8, -2
	s_ashr_i32 s5, s4, 31
	s_lshl_b64 s[4:5], s[4:5], 11
	s_add_u32 s4, s1, s4
	s_addc_u32 s5, s16, s5
	s_add_i32 s22, s8, -1
	s_ashr_i32 s23, s22, 31
	s_lshl_b64 s[22:23], s[22:23], 11
	s_add_u32 s30, s1, s22
	s_addc_u32 s31, s16, s23
	s_ashr_i32 s9, s8, 31
	s_lshl_b64 s[22:23], s[8:9], 11
	s_add_u32 s34, s1, s22
	s_addc_u32 s35, s16, s23
	s_addk_i32 s0, 0x800
	s_addk_i32 s8, 0x2000
	s_waitcnt vmcnt(19)
	v_pk_add_f32 v[52:53], v[52:53], 1.0 op_sel_hi:[1,0]
	v_pk_add_f32 v[50:51], v[50:51], 1.0 op_sel_hi:[1,0]
	s_waitcnt vmcnt(18)
	v_pk_fma_f32 v[44:45], v[44:45], v[52:53], v[56:57]
	v_pk_fma_f32 v[42:43], v[42:43], v[50:51], v[54:55]
	v_bfe_u32 v84, v44, 16, 1
	v_bfe_u32 v82, v42, 16, 1
	v_bfe_u32 v83, v43, 16, 1
	s_waitcnt vmcnt(11)
	v_pk_fma_f32 v[60:61], v[60:61], v[52:53], v[56:57]
	v_pk_fma_f32 v[58:59], v[58:59], v[50:51], v[54:55]
	v_bfe_u32 v85, v45, 16, 1
	s_waitcnt vmcnt(10)
	v_pk_fma_f32 v[64:65], v[64:65], v[52:53], v[56:57]
	v_pk_fma_f32 v[62:63], v[62:63], v[50:51], v[54:55]
	s_waitcnt vmcnt(9)
	v_pk_fma_f32 v[52:53], v[68:69], v[52:53], v[56:57]
	v_pk_fma_f32 v[50:51], v[66:67], v[50:51], v[54:55]
	v_add3_u32 v42, v42, v82, s20
	v_add3_u32 v44, v44, v84, s20
	v_bfe_u32 v54, v58, 16, 1
	v_bfe_u32 v56, v60, 16, 1
	v_add3_u32 v43, v43, v83, s20
	v_add3_u32 v45, v45, v85, s20
	v_bfe_u32 v55, v59, 16, 1
	v_bfe_u32 v57, v61, 16, 1
	v_bfe_u32 v66, v62, 16, 1
	v_bfe_u32 v68, v64, 16, 1
	v_bfe_u32 v82, v50, 16, 1
	v_bfe_u32 v84, v52, 16, 1
	v_lshrrev_b32_e32 v42, 16, v42
	v_lshrrev_b32_e32 v44, 16, v44
	v_add3_u32 v54, v58, v54, s20
	v_add3_u32 v56, v60, v56, s20
	v_bfe_u32 v67, v63, 16, 1
	v_bfe_u32 v69, v65, 16, 1
	v_bfe_u32 v83, v51, 16, 1
	v_bfe_u32 v85, v53, 16, 1
	v_add3_u32 v55, v59, v55, s20
	v_add3_u32 v57, v61, v57, s20
	v_add3_u32 v58, v62, v66, s20
	v_add3_u32 v60, v64, v68, s20
	v_add3_u32 v50, v50, v82, s20
	v_add3_u32 v52, v52, v84, s20
	v_and_or_b32 v42, v43, s21, v42
	v_and_or_b32 v43, v45, s21, v44
	v_lshrrev_b32_e32 v44, 16, v54
	v_lshrrev_b32_e32 v45, 16, v56
	v_add3_u32 v59, v63, v67, s20
	v_add3_u32 v61, v65, v69, s20
	v_add3_u32 v51, v51, v83, s20
	v_add3_u32 v53, v53, v85, s20
	v_lshrrev_b32_e32 v54, 16, v58
	v_lshrrev_b32_e32 v56, 16, v60
	v_lshrrev_b32_e32 v50, 16, v50
	v_lshrrev_b32_e32 v52, 16, v52
	global_store_dwordx2 v1, v[42:43], s[14:15]
	v_and_or_b32 v42, v55, s21, v44
	v_and_or_b32 v43, v57, s21, v45
	v_and_or_b32 v44, v59, s21, v54
	v_and_or_b32 v45, v61, s21, v56
	v_and_or_b32 v50, v51, s21, v50
	v_and_or_b32 v51, v53, s21, v52
	global_store_dwordx2 v1, v[42:43], s[4:5]
	global_store_dwordx2 v1, v[44:45], s[30:31]
	global_store_dwordx2 v1, v[50:51], s[34:35]
	s_nop 0
	s_waitcnt vmcnt(6)
	v_pk_add_f32 v[102:103], v[102:103], 1.0 op_sel_hi:[1,0]
	v_pk_add_f32 v[100:101], v[100:101], 1.0 op_sel_hi:[1,0]
	v_pk_fma_f32 v[48:49], v[48:49], v[102:103], v[106:107]
	v_pk_fma_f32 v[46:47], v[46:47], v[100:101], v[104:105]
	v_pk_fma_f32 v[54:55], v[72:73], v[102:103], v[106:107]
	v_pk_fma_f32 v[56:57], v[70:71], v[100:101], v[104:105]
	v_pk_fma_f32 v[58:59], v[76:77], v[102:103], v[106:107]
	v_pk_fma_f32 v[60:61], v[74:75], v[100:101], v[104:105]
	v_pk_fma_f32 v[102:103], v[80:81], v[102:103], v[106:107]
	v_pk_fma_f32 v[100:101], v[78:79], v[100:101], v[104:105]
	v_bfe_u32 v104, v46, 16, 1
	v_bfe_u32 v106, v48, 16, 1
	v_bfe_u32 v105, v47, 16, 1
	v_bfe_u32 v107, v49, 16, 1
	v_bfe_u32 v62, v56, 16, 1
	v_bfe_u32 v63, v57, 16, 1
	v_bfe_u32 v64, v54, 16, 1
	v_bfe_u32 v66, v60, 16, 1
	v_bfe_u32 v68, v58, 16, 1
	v_bfe_u32 v69, v59, 16, 1
	v_bfe_u32 v70, v100, 16, 1
	v_bfe_u32 v71, v101, 16, 1
	v_bfe_u32 v72, v102, 16, 1
	v_bfe_u32 v73, v103, 16, 1
	v_add3_u32 v46, v46, v104, s20
	v_add3_u32 v48, v48, v106, s20
	v_bfe_u32 v65, v55, 16, 1
	v_bfe_u32 v67, v61, 16, 1
	v_add3_u32 v47, v47, v105, s20
	v_add3_u32 v49, v49, v107, s20
	v_add3_u32 v104, v56, v62, s20
	v_add3_u32 v105, v57, v63, s20
	v_add3_u32 v106, v54, v64, s20
	v_add3_u32 v54, v60, v66, s20
	v_add3_u32 v56, v58, v68, s20
	v_add3_u32 v57, v59, v69, s20
	v_add3_u32 v100, v100, v70, s20
	v_add3_u32 v58, v101, v71, s20
	v_add3_u32 v101, v102, v72, s20
	v_add3_u32 v59, v103, v73, s20
	v_lshrrev_b32_e32 v102, 16, v46
	v_lshrrev_b32_e32 v103, 16, v48
	v_add3_u32 v107, v55, v65, s20
	v_add3_u32 v55, v61, v67, s20
	v_lshrrev_b32_e32 v46, 16, v104
	v_lshrrev_b32_e32 v48, 16, v106
	v_lshrrev_b32_e32 v104, 16, v54
	v_lshrrev_b32_e32 v106, 16, v56
	v_lshrrev_b32_e32 v54, 16, v100
	v_lshrrev_b32_e32 v56, 16, v101
	v_and_or_b32 v100, v47, s21, v102
	v_and_or_b32 v101, v49, s21, v103
	v_and_or_b32 v102, v105, s21, v46
	v_and_or_b32 v103, v107, s21, v48
	v_and_or_b32 v46, v55, s21, v104
	v_and_or_b32 v47, v57, s21, v106
	v_and_or_b32 v48, v58, s21, v54
	v_and_or_b32 v49, v59, s21, v56
	global_store_dwordx2 v1, v[100:101], s[14:15] offset:512
	global_store_dwordx2 v1, v[102:103], s[4:5] offset:512
	global_store_dwordx2 v1, v[46:47], s[30:31] offset:512
	global_store_dwordx2 v1, v[48:49], s[34:35] offset:512
	s_nop 0
	s_waitcnt vmcnt(9)
	v_pk_add_f32 v[110:111], v[110:111], 1.0 op_sel_hi:[1,0]
	v_pk_add_f32 v[108:109], v[108:109], 1.0 op_sel_hi:[1,0]
	v_pk_fma_f32 v[24:25], v[24:25], v[110:111], v[114:115]
	v_pk_fma_f32 v[22:23], v[22:23], v[108:109], v[112:113]
	v_pk_fma_f32 v[32:33], v[32:33], v[110:111], v[114:115]
	v_pk_fma_f32 v[30:31], v[30:31], v[108:109], v[112:113]
	v_pk_fma_f32 v[28:29], v[28:29], v[110:111], v[114:115]
	v_pk_fma_f32 v[26:27], v[26:27], v[108:109], v[112:113]
	v_pk_fma_f32 v[20:21], v[20:21], v[110:111], v[114:115]
	v_pk_fma_f32 v[18:19], v[18:19], v[108:109], v[112:113]
	v_bfe_u32 v108, v22, 16, 1
	v_bfe_u32 v110, v24, 16, 1
	v_bfe_u32 v109, v23, 16, 1
	v_bfe_u32 v111, v25, 16, 1
	v_bfe_u32 v112, v30, 16, 1
	v_bfe_u32 v114, v32, 16, 1
	v_bfe_u32 v50, v26, 16, 1
	v_bfe_u32 v52, v28, 16, 1
	v_bfe_u32 v54, v18, 16, 1
	v_bfe_u32 v55, v19, 16, 1
	v_bfe_u32 v56, v20, 16, 1
	v_bfe_u32 v57, v21, 16, 1
	v_add3_u32 v22, v22, v108, s20
	v_add3_u32 v24, v24, v110, s20
	v_bfe_u32 v113, v31, 16, 1
	v_bfe_u32 v115, v33, 16, 1
	v_bfe_u32 v51, v27, 16, 1
	v_bfe_u32 v53, v29, 16, 1
	v_add3_u32 v23, v23, v109, s20
	v_add3_u32 v25, v25, v111, s20
	v_add3_u32 v30, v30, v112, s20
	v_add3_u32 v32, v32, v114, s20
	v_add3_u32 v26, v26, v50, s20
	v_add3_u32 v28, v28, v52, s20
	v_add3_u32 v18, v18, v54, s20
	v_add3_u32 v108, v19, v55, s20
	v_add3_u32 v19, v20, v56, s20
	v_add3_u32 v109, v21, v57, s20
	v_lshrrev_b32_e32 v20, 16, v22
	v_lshrrev_b32_e32 v21, 16, v24
	v_add3_u32 v31, v31, v113, s20
	v_add3_u32 v33, v33, v115, s20
	v_add3_u32 v27, v27, v51, s20
	v_add3_u32 v29, v29, v53, s20
	v_lshrrev_b32_e32 v22, 16, v30
	v_lshrrev_b32_e32 v24, 16, v32
	v_lshrrev_b32_e32 v26, 16, v26
	v_lshrrev_b32_e32 v28, 16, v28
	v_lshrrev_b32_e32 v30, 16, v18
	v_lshrrev_b32_e32 v32, 16, v19
	v_and_or_b32 v18, v23, s21, v20
	v_and_or_b32 v19, v25, s21, v21
	v_and_or_b32 v20, v31, s21, v22
	v_and_or_b32 v21, v33, s21, v24
	v_and_or_b32 v22, v27, s21, v26
	v_and_or_b32 v23, v29, s21, v28
	v_and_or_b32 v24, v108, s21, v30
	v_and_or_b32 v25, v109, s21, v32
	global_store_dwordx2 v1, v[18:19], s[14:15] offset:1024
	global_store_dwordx2 v1, v[20:21], s[4:5] offset:1024
	global_store_dwordx2 v1, v[22:23], s[30:31] offset:1024
	global_store_dwordx2 v1, v[24:25], s[34:35] offset:1024
	s_nop 0
	s_waitcnt vmcnt(12)
	v_pk_add_f32 v[118:119], v[118:119], 1.0 op_sel_hi:[1,0]
	v_pk_add_f32 v[116:117], v[116:117], 1.0 op_sel_hi:[1,0]
	v_pk_fma_f32 v[4:5], v[4:5], v[118:119], v[122:123]
	v_pk_fma_f32 v[2:3], v[2:3], v[116:117], v[120:121]
	v_pk_fma_f32 v[8:9], v[8:9], v[118:119], v[122:123]
	v_pk_fma_f32 v[6:7], v[6:7], v[116:117], v[120:121]
	v_pk_fma_f32 v[12:13], v[12:13], v[118:119], v[122:123]
	v_pk_fma_f32 v[10:11], v[10:11], v[116:117], v[120:121]
	v_pk_fma_f32 v[16:17], v[16:17], v[118:119], v[122:123]
	v_pk_fma_f32 v[14:15], v[14:15], v[116:117], v[120:121]
	v_bfe_u32 v116, v2, 16, 1
	v_bfe_u32 v118, v4, 16, 1
	v_bfe_u32 v117, v3, 16, 1
	v_bfe_u32 v119, v5, 16, 1
	v_bfe_u32 v120, v6, 16, 1
	v_bfe_u32 v122, v8, 16, 1
	v_bfe_u32 v26, v10, 16, 1
	v_bfe_u32 v28, v12, 16, 1
	v_bfe_u32 v30, v14, 16, 1
	v_bfe_u32 v32, v16, 16, 1
	v_add3_u32 v2, v2, v116, s20
	v_add3_u32 v4, v4, v118, s20
	v_bfe_u32 v121, v7, 16, 1
	v_bfe_u32 v123, v9, 16, 1
	v_bfe_u32 v27, v11, 16, 1
	v_bfe_u32 v29, v13, 16, 1
	v_bfe_u32 v31, v15, 16, 1
	v_bfe_u32 v33, v17, 16, 1
	v_add3_u32 v3, v3, v117, s20
	v_add3_u32 v5, v5, v119, s20
	v_add3_u32 v6, v6, v120, s20
	v_add3_u32 v8, v8, v122, s20
	v_add3_u32 v10, v10, v26, s20
	v_add3_u32 v12, v12, v28, s20
	v_add3_u32 v14, v14, v30, s20
	v_add3_u32 v16, v16, v32, s20
	v_lshrrev_b32_e32 v2, 16, v2
	v_lshrrev_b32_e32 v4, 16, v4
	v_add3_u32 v7, v7, v121, s20
	v_add3_u32 v9, v9, v123, s20
	v_add3_u32 v11, v11, v27, s20
	v_add3_u32 v13, v13, v29, s20
	v_add3_u32 v15, v15, v31, s20
	v_add3_u32 v17, v17, v33, s20
	v_lshrrev_b32_e32 v6, 16, v6
	v_lshrrev_b32_e32 v8, 16, v8
	v_lshrrev_b32_e32 v10, 16, v10
	v_lshrrev_b32_e32 v12, 16, v12
	v_lshrrev_b32_e32 v14, 16, v14
	v_lshrrev_b32_e32 v16, 16, v16
	v_and_or_b32 v2, v3, s21, v2
	v_and_or_b32 v3, v5, s21, v4
	v_and_or_b32 v4, v7, s21, v6
	v_and_or_b32 v5, v9, s21, v8
	v_and_or_b32 v6, v11, s21, v10
	v_and_or_b32 v7, v13, s21, v12
	v_and_or_b32 v8, v15, s21, v14
	v_and_or_b32 v9, v17, s21, v16
	global_store_dwordx2 v1, v[2:3], s[14:15] offset:1536
	global_store_dwordx2 v1, v[4:5], s[4:5] offset:1536
	global_store_dwordx2 v1, v[6:7], s[30:31] offset:1536
	global_store_dwordx2 v1, v[8:9], s[34:35] offset:1536
	s_cbranch_vccnz .LBB0_119
